# up-GEMM epilogue: conv weights fetched with one load per lane and broadcast through the wave's own free LDS ring slot (16 ds_read_b128) instead of 16 global loads per lane
# speedup vs baseline: 1.0047x; 1.0028x over previous
;     __device__ __forceinline__ void operator()(f32x4 (&acc)[2][2][4][2], const Unit& u, int wr, int wc, int fr, int fq, const LAS float* rtab) const {
;         const int c0 = u.pn * 128 + wc * 32 + 8 * fq;
; #pragma unroll
;         for (int ai = 0; ai < 2; ++ai)
; #pragma unroll
;             for (int m = 0; m < 4; ++m) { const float r = rtab[ai * HALF + wr * 64 + m * 16 + fr];
; #pragma unroll
;                 for (int bj = 0; bj < 2; ++bj)
; #pragma unroll
;                     for (int n = 0; n < 2; ++n) acc[ai][bj][m][n] = acc[ai][bj][m][n] * r; }
; #pragma unroll
;         for (int ai = 0; ai < 2; ++ai) {
;             const int blk = (u.pm * BM + ai * HALF + wr * 64) >> 6;
;             if (fr < 2) { bf16_t* rp = raw + ((size_t)blk * 4 + fr) * UP_N + c0;
;                 const f32x4 g0 = acc[ai][0][0][0], g1 = acc[ai][0][0][1], u0 = acc[ai][1][0][0], u1 = acc[ai][1][0][1];
;                 u32x4 w; w.x = cvt_pk_bf16(g0[0], g0[1]); w.y = cvt_pk_bf16(g0[2], g0[3]); w.z = cvt_pk_bf16(g1[0], g1[1]); w.w = cvt_pk_bf16(g1[2], g1[3]); *(u32x4*)rp = w;
;                 w.x = cvt_pk_bf16(u0[0], u0[1]); w.y = cvt_pk_bf16(u0[2], u0[3]); w.z = cvt_pk_bf16(u1[0], u1[1]); w.w = cvt_pk_bf16(u1[2], u1[3]); *(u32x4*)(rp + DFF) = w; }
;             if (fr >= 14) { bf16_t* rp = raw + ((size_t)blk * 4 + (fr - 12)) * UP_N + c0;
;                 const f32x4 g0 = acc[ai][0][3][0], g1 = acc[ai][0][3][1], u0 = acc[ai][1][3][0], u1 = acc[ai][1][3][1];
;                 u32x4 w; w.x = cvt_pk_bf16(g0[0], g0[1]); w.y = cvt_pk_bf16(g0[2], g0[3]); w.z = cvt_pk_bf16(g1[0], g1[1]); w.w = cvt_pk_bf16(g1[2], g1[3]); *(u32x4*)rp = w;
;                 w.x = cvt_pk_bf16(u0[0], u0[1]); w.y = cvt_pk_bf16(u0[2], u0[3]); w.z = cvt_pk_bf16(u1[0], u1[1]); w.w = cvt_pk_bf16(u1[2], u1[3]); *(u32x4*)(rp + DFF) = w; }
;         }
;         u32x2 ypk[2][4];
; #pragma unroll
;         for (int n = 0; n < 2; ++n) {
;             const int cn = c0 + 4 * n;
;             const f32x4 wg0 = *(const f32x4*)(cw + cn), wg1 = *(const f32x4*)(cw + UP_N + cn), wg2 = *(const f32x4*)(cw + 2 * UP_N + cn), bg = *(const f32x4*)(cb + cn);
;             const f32x4 wu0 = *(const f32x4*)(cw + DFF + cn), wu1 = *(const f32x4*)(cw + UP_N + DFF + cn), wu2 = *(const f32x4*)(cw + 2 * UP_N + DFF + cn), bu = *(const f32x4*)(cb + DFF + cn);
.LBB0_839:
	v_lshl_add_u32 v252, s1, 10, v192
	v_mad_u32_u24 v252, v134, 12, v252
	ds_read_b128 v[228:231], v252
	ds_read_b128 v[232:235], v252 offset:512
	v_lshl_or_b32 v213, s0, 7, v193
	v_lshlrev_b32_e32 v253, 2, v213
	v_and_b32_e32 v217, 63, v208
	v_lshrrev_b32_e32 v142, 1, v134
	v_and_b32_e32 v143, 1, v134
	v_and_b32_e32 v178, 3, v142
	v_cmp_eq_u32_e64 s[56:57], 3, v178
	v_cmp_lt_u32_e64 s[54:55], 3, v142
	v_mul_u32_u24_e32 v210, 0xb000, v178
	v_mov_b32_e32 v211, 0
	v_cndmask_b32_e64 v210, v210, 0, s[56:57]
	v_lshl_add_u32 v210, v143, 4, v210
	v_lshl_add_u32 v210, v213, 2, v210
	v_add_u32_e32 v179, 0x5800, v210
	v_cndmask_b32_e64 v210, v210, v179, s[54:55]
	v_mov_b32_e32 v218, s34
	v_mov_b32_e32 v219, s35
	v_mov_b32_e32 v252, s36
	v_mov_b32_e32 v253, s37
	v_cndmask_b32_e64 v218, v218, v252, s[56:57]
	v_cndmask_b32_e64 v219, v219, v253, s[56:57]
	v_lshl_add_u64 v[210:211], v[218:219], 0, v[210:211]
	global_load_dwordx4 v[224:227], v[210:211], off
	v_lshl_add_u32 v195, v217, 4, s19
	v_and_b32_e32 v212, 0x30, v217
	v_lshl_add_u32 v212, v212, 4, s19
	s_waitcnt lgkmcnt(0)
	v_pk_mul_f32 v[124:125], v[124:125], v[228:229] op_sel_hi:[1,0]
	v_pk_mul_f32 v[126:127], v[126:127], v[228:229] op_sel_hi:[1,0]
	v_pk_mul_f32 v[120:121], v[120:121], v[228:229] op_sel_hi:[1,0]
	v_pk_mul_f32 v[122:123], v[122:123], v[228:229] op_sel_hi:[1,0]
	v_pk_mul_f32 v[116:117], v[116:117], v[228:229] op_sel_hi:[1,0]
	v_pk_mul_f32 v[118:119], v[118:119], v[228:229] op_sel_hi:[1,0]
	v_pk_mul_f32 v[112:113], v[112:113], v[228:229] op_sel_hi:[1,0]
	v_pk_mul_f32 v[114:115], v[114:115], v[228:229] op_sel_hi:[1,0]
	v_pk_mul_f32 v[68:69], v[68:69], v[228:229] op_sel:[0,1] op_sel_hi:[1,1]
	v_pk_mul_f32 v[70:71], v[70:71], v[228:229] op_sel:[0,1] op_sel_hi:[1,1]
	v_pk_mul_f32 v[64:65], v[64:65], v[228:229] op_sel:[0,1] op_sel_hi:[1,1]
	v_pk_mul_f32 v[66:67], v[66:67], v[228:229] op_sel:[0,1] op_sel_hi:[1,1]
	v_pk_mul_f32 v[52:53], v[52:53], v[228:229] op_sel:[0,1] op_sel_hi:[1,1]
	v_pk_mul_f32 v[54:55], v[54:55], v[228:229] op_sel:[0,1] op_sel_hi:[1,1]
	v_pk_mul_f32 v[48:49], v[48:49], v[228:229] op_sel:[0,1] op_sel_hi:[1,1]
	v_pk_mul_f32 v[50:51], v[50:51], v[228:229] op_sel:[0,1] op_sel_hi:[1,1]
	v_pk_mul_f32 v[60:61], v[60:61], v[230:231] op_sel_hi:[1,0]
	v_pk_mul_f32 v[62:63], v[62:63], v[230:231] op_sel_hi:[1,0]
	v_pk_mul_f32 v[20:21], v[20:21], v[230:231] op_sel_hi:[1,0]
	v_pk_mul_f32 v[22:23], v[22:23], v[230:231] op_sel_hi:[1,0]
	v_pk_mul_f32 v[44:45], v[44:45], v[230:231] op_sel_hi:[1,0]
	v_pk_mul_f32 v[46:47], v[46:47], v[230:231] op_sel_hi:[1,0]
	v_pk_mul_f32 v[16:17], v[16:17], v[230:231] op_sel_hi:[1,0]
	v_pk_mul_f32 v[18:19], v[18:19], v[230:231] op_sel_hi:[1,0]
	v_pk_mul_f32 v[108:109], v[108:109], v[230:231] op_sel:[0,1] op_sel_hi:[1,1]
	v_pk_mul_f32 v[110:111], v[110:111], v[230:231] op_sel:[0,1] op_sel_hi:[1,1]
	v_pk_mul_f32 v[104:105], v[104:105], v[230:231] op_sel:[0,1] op_sel_hi:[1,1]
	v_pk_mul_f32 v[106:107], v[106:107], v[230:231] op_sel:[0,1] op_sel_hi:[1,1]
	v_pk_mul_f32 v[100:101], v[100:101], v[230:231] op_sel:[0,1] op_sel_hi:[1,1]
	v_pk_mul_f32 v[102:103], v[102:103], v[230:231] op_sel:[0,1] op_sel_hi:[1,1]
	v_pk_mul_f32 v[96:97], v[96:97], v[230:231] op_sel:[0,1] op_sel_hi:[1,1]
	v_pk_mul_f32 v[98:99], v[98:99], v[230:231] op_sel:[0,1] op_sel_hi:[1,1]
	v_pk_mul_f32 v[92:93], v[92:93], v[232:233] op_sel_hi:[1,0]
	v_pk_mul_f32 v[94:95], v[94:95], v[232:233] op_sel_hi:[1,0]
	v_pk_mul_f32 v[88:89], v[88:89], v[232:233] op_sel_hi:[1,0]
	v_pk_mul_f32 v[90:91], v[90:91], v[232:233] op_sel_hi:[1,0]
	v_pk_mul_f32 v[84:85], v[84:85], v[232:233] op_sel_hi:[1,0]
	v_pk_mul_f32 v[86:87], v[86:87], v[232:233] op_sel_hi:[1,0]
	v_pk_mul_f32 v[80:81], v[80:81], v[232:233] op_sel_hi:[1,0]
	v_pk_mul_f32 v[82:83], v[82:83], v[232:233] op_sel_hi:[1,0]
	v_pk_mul_f32 v[36:37], v[36:37], v[232:233] op_sel:[0,1] op_sel_hi:[1,1]
	v_pk_mul_f32 v[38:39], v[38:39], v[232:233] op_sel:[0,1] op_sel_hi:[1,1]
	v_pk_mul_f32 v[12:13], v[12:13], v[232:233] op_sel:[0,1] op_sel_hi:[1,1]
	v_pk_mul_f32 v[14:15], v[14:15], v[232:233] op_sel:[0,1] op_sel_hi:[1,1]
	v_pk_mul_f32 v[28:29], v[28:29], v[232:233] op_sel:[0,1] op_sel_hi:[1,1]
	v_pk_mul_f32 v[30:31], v[30:31], v[232:233] op_sel:[0,1] op_sel_hi:[1,1]
	v_pk_mul_f32 v[8:9], v[8:9], v[232:233] op_sel:[0,1] op_sel_hi:[1,1]
	v_pk_mul_f32 v[10:11], v[10:11], v[232:233] op_sel:[0,1] op_sel_hi:[1,1]
	v_pk_mul_f32 v[32:33], v[32:33], v[234:235] op_sel_hi:[1,0]
	v_pk_mul_f32 v[34:35], v[34:35], v[234:235] op_sel_hi:[1,0]
	v_pk_mul_f32 v[4:5], v[4:5], v[234:235] op_sel_hi:[1,0]
	v_pk_mul_f32 v[6:7], v[6:7], v[234:235] op_sel_hi:[1,0]
	v_pk_mul_f32 v[24:25], v[24:25], v[234:235] op_sel_hi:[1,0]
	v_pk_mul_f32 v[26:27], v[26:27], v[234:235] op_sel_hi:[1,0]
	v_pk_mul_f32 v[0:1], v[0:1], v[234:235] op_sel_hi:[1,0]
	v_pk_mul_f32 v[2:3], v[2:3], v[234:235] op_sel_hi:[1,0]
	v_pk_mul_f32 v[76:77], v[76:77], v[234:235] op_sel:[0,1] op_sel_hi:[1,1]
	v_pk_mul_f32 v[78:79], v[78:79], v[234:235] op_sel:[0,1] op_sel_hi:[1,1]
	v_pk_mul_f32 v[56:57], v[56:57], v[234:235] op_sel:[0,1] op_sel_hi:[1,1]
	v_pk_mul_f32 v[58:59], v[58:59], v[234:235] op_sel:[0,1] op_sel_hi:[1,1]
	v_pk_mul_f32 v[72:73], v[72:73], v[234:235] op_sel:[0,1] op_sel_hi:[1,1]
	v_pk_mul_f32 v[74:75], v[74:75], v[234:235] op_sel:[0,1] op_sel_hi:[1,1]
	v_pk_mul_f32 v[40:41], v[40:41], v[234:235] op_sel:[0,1] op_sel_hi:[1,1]
	v_pk_mul_f32 v[42:43], v[42:43], v[234:235] op_sel:[0,1] op_sel_hi:[1,1]
	v_lshlrev_b32_e32 v235, 1, v213
	s_lshl_b32 s0, s18, 8
	s_add_i32 s0, s0, s69
	v_lshl_add_u32 v234, v134, 2, s0
	v_mul_lo_u32 v234, v234, s89
	v_add_u32_e32 v234, v234, v235
	v_cmp_eq_u32_e64 s[54:55], 0, v134
; __device__ __forceinline__ unsigned cvt_pk_bf16(float lo, float hi) { unsigned r; asm volatile("v_cvt_pk_bf16_f32 %0, %1, %2" : "=v"(r) : "v"(lo), "v"(hi)); return r; }
;     __device__ __forceinline__ void operator()(f32x4 (&acc)[2][2][4][2], const Unit& u, int wr, int wc, int fr, int fq, const LAS float* rtab) const {
;     ...
; #pragma unroll
;         for (int ai = 0; ai < 2; ++ai) {
;             const int blk = (u.pm * BM + ai * HALF + wr * 64) >> 6;
;             if (fr < 2) { bf16_t* rp = raw + ((size_t)blk * 4 + fr) * UP_N + c0;
;                 const f32x4 g0 = acc[ai][0][0][0], g1 = acc[ai][0][0][1], u0 = acc[ai][1][0][0], u1 = acc[ai][1][0][1];
;                 u32x4 w; w.x = cvt_pk_bf16(g0[0], g0[1]); w.y = cvt_pk_bf16(g0[2], g0[3]); w.z = cvt_pk_bf16(g1[0], g1[1]); w.w = cvt_pk_bf16(g1[2], g1[3]); *(u32x4*)rp = w;
;                 w.x = cvt_pk_bf16(u0[0], u0[1]); w.y = cvt_pk_bf16(u0[2], u0[3]); w.z = cvt_pk_bf16(u1[0], u1[1]); w.w = cvt_pk_bf16(u1[2], u1[3]); *(u32x4*)(rp + DFF) = w; }
;             if (fr >= 14) { bf16_t* rp = raw + ((size_t)blk * 4 + (fr - 12)) * UP_N + c0;
;                 const f32x4 g0 = acc[ai][0][3][0], g1 = acc[ai][0][3][1], u0 = acc[ai][1][3][0], u1 = acc[ai][1][3][1];
;                 u32x4 w; w.x = cvt_pk_bf16(g0[0], g0[1]); w.y = cvt_pk_bf16(g0[2], g0[3]); w.z = cvt_pk_bf16(g1[0], g1[1]); w.w = cvt_pk_bf16(g1[2], g1[3]); *(u32x4*)rp = w;
;                 w.x = cvt_pk_bf16(u0[0], u0[1]); w.y = cvt_pk_bf16(u0[2], u0[3]); w.z = cvt_pk_bf16(u1[0], u1[1]); w.w = cvt_pk_bf16(u1[2], u1[3]); *(u32x4*)(rp + DFF) = w; }
;         }
;         u32x2 ypk[2][4];
; #pragma unroll
;         for (int n = 0; n < 2; ++n) {
;             const int cn = c0 + 4 * n;
;             const f32x4 wg0 = *(const f32x4*)(cw + cn), wg1 = *(const f32x4*)(cw + UP_N + cn), wg2 = *(const f32x4*)(cw + 2 * UP_N + cn), bg = *(const f32x4*)(cb + cn);
;             const f32x4 wu0 = *(const f32x4*)(cw + DFF + cn), wu1 = *(const f32x4*)(cw + UP_N + DFF + cn), wu2 = *(const f32x4*)(cw + 2 * UP_N + DFF + cn), bu = *(const f32x4*)(cb + DFF + cn);
	v_cmp_eq_u32_e64 s[56:57], 15, v134
	s_lshl_b32 s0, s18, 4
	s_lshr_b32 s1, s69, 4
	s_add_i32 s0, s0, s1
	s_add_i32 s1, s0, 0
	s_mul_i32 s1, s1, s88
	s_add_u32 s58, s30, s1
	s_addc_u32 s59, s31, 0
	s_mov_b64 exec, s[54:55]
	v_cvt_pk_bf16_f32 v244, v124, v125
	v_cvt_pk_bf16_f32 v245, v126, v127
	v_cvt_pk_bf16_f32 v246, v120, v121
	v_cvt_pk_bf16_f32 v247, v122, v123
	v_cvt_pk_bf16_f32 v248, v116, v117
	v_cvt_pk_bf16_f32 v249, v118, v119
	v_cvt_pk_bf16_f32 v250, v112, v113
	v_cvt_pk_bf16_f32 v251, v114, v115
	global_store_dwordx4 v235, v[244:247], s[58:59]
	s_add_u32 s58, s58, 0x2c00
	s_addc_u32 s59, s59, 0
	global_store_dwordx4 v235, v[248:251], s[58:59]
	s_add_i32 s1, s0, 1
	s_mul_i32 s1, s1, s88
	s_add_u32 s58, s30, s1
	s_addc_u32 s59, s31, 0
	s_mov_b64 exec, s[54:55]
	v_cvt_pk_bf16_f32 v236, v68, v69
	v_cvt_pk_bf16_f32 v237, v70, v71
	v_cvt_pk_bf16_f32 v238, v64, v65
	v_cvt_pk_bf16_f32 v239, v66, v67
	v_cvt_pk_bf16_f32 v240, v52, v53
	v_cvt_pk_bf16_f32 v241, v54, v55
	v_cvt_pk_bf16_f32 v242, v48, v49
	v_cvt_pk_bf16_f32 v243, v50, v51
	global_store_dwordx4 v235, v[236:239], s[58:59]
	s_add_u32 s58, s58, 0x2c00
	s_addc_u32 s59, s59, 0
	global_store_dwordx4 v235, v[240:243], s[58:59]
	s_add_i32 s1, s0, 2
	s_mul_i32 s1, s1, s88
	s_add_u32 s58, s30, s1
	s_addc_u32 s59, s31, 0
	s_mov_b64 exec, s[56:57]
	v_cvt_pk_bf16_f32 v244, v60, v61
	v_cvt_pk_bf16_f32 v245, v62, v63
	v_cvt_pk_bf16_f32 v246, v20, v21
	v_cvt_pk_bf16_f32 v247, v22, v23
	v_cvt_pk_bf16_f32 v248, v44, v45
	v_cvt_pk_bf16_f32 v249, v46, v47
	v_cvt_pk_bf16_f32 v250, v16, v17
	v_cvt_pk_bf16_f32 v251, v18, v19
	global_store_dwordx4 v235, v[244:247], s[58:59]
	s_add_u32 s58, s58, 0x2c00
	s_addc_u32 s59, s59, 0
	global_store_dwordx4 v235, v[248:251], s[58:59]
	s_add_i32 s1, s0, 3
	s_mul_i32 s1, s1, s88
	s_add_u32 s58, s30, s1
	s_addc_u32 s59, s31, 0
	s_mov_b64 exec, s[56:57]
	v_cvt_pk_bf16_f32 v236, v108, v109
	v_cvt_pk_bf16_f32 v237, v110, v111
	v_cvt_pk_bf16_f32 v238, v104, v105
	v_cvt_pk_bf16_f32 v239, v106, v107
	v_cvt_pk_bf16_f32 v240, v100, v101
	v_cvt_pk_bf16_f32 v241, v102, v103
	v_cvt_pk_bf16_f32 v242, v96, v97
	v_cvt_pk_bf16_f32 v243, v98, v99
	global_store_dwordx4 v235, v[236:239], s[58:59]
	s_add_u32 s58, s58, 0x2c00
	s_addc_u32 s59, s59, 0
	global_store_dwordx4 v235, v[240:243], s[58:59]
	s_add_i32 s1, s0, 8
	s_mul_i32 s1, s1, s88
	s_add_u32 s58, s30, s1
	s_addc_u32 s59, s31, 0
	s_mov_b64 exec, s[54:55]
	v_cvt_pk_bf16_f32 v244, v92, v93
	v_cvt_pk_bf16_f32 v245, v94, v95
	v_cvt_pk_bf16_f32 v246, v88, v89
	v_cvt_pk_bf16_f32 v247, v90, v91
	v_cvt_pk_bf16_f32 v248, v84, v85
	v_cvt_pk_bf16_f32 v249, v86, v87
	v_cvt_pk_bf16_f32 v250, v80, v81
	v_cvt_pk_bf16_f32 v251, v82, v83
	global_store_dwordx4 v235, v[244:247], s[58:59]
	s_add_u32 s58, s58, 0x2c00
	s_addc_u32 s59, s59, 0
	global_store_dwordx4 v235, v[248:251], s[58:59]
	s_add_i32 s1, s0, 9
	s_mul_i32 s1, s1, s88
	s_add_u32 s58, s30, s1
	s_addc_u32 s59, s31, 0
	s_mov_b64 exec, s[54:55]
	v_cvt_pk_bf16_f32 v236, v36, v37
	v_cvt_pk_bf16_f32 v237, v38, v39
	v_cvt_pk_bf16_f32 v238, v12, v13
	v_cvt_pk_bf16_f32 v239, v14, v15
	v_cvt_pk_bf16_f32 v240, v28, v29
	v_cvt_pk_bf16_f32 v241, v30, v31
	v_cvt_pk_bf16_f32 v242, v8, v9
	v_cvt_pk_bf16_f32 v243, v10, v11
	global_store_dwordx4 v235, v[236:239], s[58:59]
	s_add_u32 s58, s58, 0x2c00
	s_addc_u32 s59, s59, 0
	global_store_dwordx4 v235, v[240:243], s[58:59]
	s_add_i32 s1, s0, 10
	s_mul_i32 s1, s1, s88
	s_add_u32 s58, s30, s1
	s_addc_u32 s59, s31, 0
	s_mov_b64 exec, s[56:57]
	v_cvt_pk_bf16_f32 v244, v32, v33
	v_cvt_pk_bf16_f32 v245, v34, v35
	v_cvt_pk_bf16_f32 v246, v4, v5
	v_cvt_pk_bf16_f32 v247, v6, v7
	v_cvt_pk_bf16_f32 v248, v24, v25
	v_cvt_pk_bf16_f32 v249, v26, v27
	v_cvt_pk_bf16_f32 v250, v0, v1
	v_cvt_pk_bf16_f32 v251, v2, v3
	global_store_dwordx4 v235, v[244:247], s[58:59]
	s_add_u32 s58, s58, 0x2c00
	s_addc_u32 s59, s59, 0
	global_store_dwordx4 v235, v[248:251], s[58:59]
	s_add_i32 s1, s0, 11
	s_mul_i32 s1, s1, s88
	s_add_u32 s58, s30, s1
	s_addc_u32 s59, s31, 0
	s_mov_b64 exec, s[56:57]
	v_cvt_pk_bf16_f32 v236, v76, v77
	v_cvt_pk_bf16_f32 v237, v78, v79
	v_cvt_pk_bf16_f32 v238, v56, v57
	v_cvt_pk_bf16_f32 v239, v58, v59
	v_cvt_pk_bf16_f32 v240, v72, v73
	v_cvt_pk_bf16_f32 v241, v74, v75
	v_cvt_pk_bf16_f32 v242, v40, v41
	v_cvt_pk_bf16_f32 v243, v42, v43
	global_store_dwordx4 v235, v[236:239], s[58:59]
	s_add_u32 s58, s58, 0x2c00
	s_addc_u32 s59, s59, 0
	global_store_dwordx4 v235, v[240:243], s[58:59]
	s_mov_b64 exec, -1
	s_waitcnt vmcnt(16)
	ds_write_b128 v195, v[224:227] offset:49152
	s_waitcnt lgkmcnt(0)
	ds_read_b128 v[144:147], v212 offset:49152
	ds_read_b128 v[152:155], v212 offset:49184
	ds_read_b128 v[160:163], v212 offset:49216
	ds_read_b128 v[168:171], v212 offset:49248
	ds_read_b128 v[180:183], v212 offset:49280
	ds_read_b128 v[188:191], v212 offset:49312
	ds_read_b128 v[200:203], v212 offset:49344
	ds_read_b128 v[220:223], v212 offset:49376
	ds_read_b128 v[148:151], v212 offset:49168
	ds_read_b128 v[156:159], v212 offset:49200
	ds_read_b128 v[164:167], v212 offset:49232
	ds_read_b128 v[172:175], v212 offset:49264
	ds_read_b128 v[184:187], v212 offset:49296
	ds_read_b128 v[196:199], v212 offset:49328
	ds_read_b128 v[204:207], v212 offset:49360
	ds_read_b128 v[224:227], v212 offset:49392
	s_waitcnt lgkmcnt(12)
; template <int CTRL> __device__ __forceinline__ float dppz(float v) { return __int_as_float(__builtin_amdgcn_update_dpp(0, __float_as_int(v), CTRL, 0xf, 0xf, true)); }
;     __device__ __forceinline__ void operator()(f32x4 (&acc)[2][2][4][2], const Unit& u, int wr, int wc, int fr, int fq, const LAS float* rtab) const {
;     ...
;                 for (int m = 0; m < 4; ++m) {
;                     float y[4];
; #pragma unroll
;                     for (int jj = 0; jj < 4; ++jj) {
;                         const float gc = acc[ai][0][m][n][jj], uc = acc[ai][1][m][n][jj];
;                         const float gb = m > 0 ? acc[ai][0][m - 1][n][jj] : 0.f, ga = m < 3 ? acc[ai][0][m + 1][n][jj] : 0.f;
;                         const float ub = m > 0 ? acc[ai][1][m - 1][n][jj] : 0.f, ua = m < 3 ? acc[ai][1][m + 1][n][jj] : 0.f;
;                         const float gp = dppz<0x111>(gc) + dppz<0x10F>(gb), gn = dppz<0x101>(gc) + dppz<0x11F>(ga);
;                         const float up = dppz<0x111>(uc) + dppz<0x10F>(ub), un = dppz<0x101>(uc) + dppz<0x11F>(ua);
;                         const float hg = wg0[jj] * gp + wg1[jj] * gc + wg2[jj] * gn + bg[jj];
;                         const float hu = wu0[jj] * up + wu1[jj] * uc + wu2[jj] * un + bu[jj];
;                         const float sg = __builtin_amdgcn_rcpf(1.f + __builtin_amdgcn_exp2f(-1.4426950408889634f * hg));
;                         y[jj] = hg * sg * hu; }
	s_mov_b32 s54, 0xbfb8aa3b
	s_mov_b32 s56, 1.0
	v_pk_fma_f32 v[142:143], v[152:153], v[124:125], v[168:169]
	v_pk_fma_f32 v[178:179], v[152:153], v[68:69], v[168:169]
	v_pk_fma_f32 v[210:211], v[152:153], v[60:61], v[168:169]
	v_pk_fma_f32 v[212:213], v[152:153], v[108:109], v[168:169]
	v_pk_fma_f32 v[142:143], v[160:161], v[68:69], v[142:143]
	v_pk_fma_f32 v[178:179], v[144:145], v[124:125], v[178:179]
	v_pk_fma_f32 v[210:211], v[144:145], v[68:69], v[210:211]
	v_pk_fma_f32 v[212:213], v[144:145], v[60:61], v[212:213]
	v_pk_fma_f32 v[178:179], v[160:161], v[60:61], v[178:179]
	v_pk_fma_f32 v[210:211], v[160:161], v[108:109], v[210:211]
	v_fmac_f32_dpp v142, v108, v144 row_shr:1 row_mask:0xf bank_mask:0xf bound_ctrl:1
	v_fmac_f32_dpp v212, v124, v160 row_shl:1 row_mask:0xf bank_mask:0xf bound_ctrl:1
	v_fmac_f32_dpp v143, v109, v145 row_shr:1 row_mask:0xf bank_mask:0xf bound_ctrl:1
	v_fmac_f32_dpp v213, v125, v161 row_shl:1 row_mask:0xf bank_mask:0xf bound_ctrl:1
	v_pk_mul_f32 v[218:219], v[142:143], s[54:55] op_sel_hi:[1,0]
	v_pk_mul_f32 v[252:253], v[178:179], s[54:55] op_sel_hi:[1,0]
	v_pk_mul_f32 v[228:229], v[210:211], s[54:55] op_sel_hi:[1,0]
	v_pk_mul_f32 v[230:231], v[212:213], s[54:55] op_sel_hi:[1,0]
	v_exp_f32_e32 v218, v218
	v_exp_f32_e32 v219, v219
	v_exp_f32_e32 v252, v252
	v_exp_f32_e32 v253, v253
	v_exp_f32_e32 v228, v228
	v_exp_f32_e32 v229, v229
	v_exp_f32_e32 v230, v230
	v_exp_f32_e32 v231, v231
	v_pk_add_f32 v[218:219], v[218:219], s[56:57] op_sel_hi:[1,0]
	v_pk_add_f32 v[252:253], v[252:253], s[56:57] op_sel_hi:[1,0]
	v_pk_add_f32 v[228:229], v[228:229], s[56:57] op_sel_hi:[1,0]
	v_pk_add_f32 v[230:231], v[230:231], s[56:57] op_sel_hi:[1,0]
	v_rcp_f32_e32 v218, v218
	v_rcp_f32_e32 v219, v219
	v_rcp_f32_e32 v252, v252
	v_rcp_f32_e32 v253, v253
	v_rcp_f32_e32 v228, v228
	v_rcp_f32_e32 v229, v229
	v_rcp_f32_e32 v230, v230
	v_rcp_f32_e32 v231, v231
	v_pk_mul_f32 v[142:143], v[142:143], v[218:219]
	v_pk_mul_f32 v[178:179], v[178:179], v[252:253]
	v_pk_mul_f32 v[210:211], v[210:211], v[228:229]
	v_pk_mul_f32 v[212:213], v[212:213], v[230:231]
	s_waitcnt lgkmcnt(8)
	v_pk_fma_f32 v[218:219], v[188:189], v[116:117], v[220:221]
	v_pk_fma_f32 v[252:253], v[188:189], v[52:53], v[220:221]
	v_pk_fma_f32 v[228:229], v[188:189], v[44:45], v[220:221]
	v_pk_fma_f32 v[230:231], v[188:189], v[100:101], v[220:221]
	v_pk_fma_f32 v[218:219], v[200:201], v[52:53], v[218:219]
	v_pk_fma_f32 v[252:253], v[180:181], v[116:117], v[252:253]
	v_pk_fma_f32 v[228:229], v[180:181], v[52:53], v[228:229]
	v_pk_fma_f32 v[230:231], v[180:181], v[44:45], v[230:231]
	v_pk_fma_f32 v[252:253], v[200:201], v[44:45], v[252:253]
	v_pk_fma_f32 v[228:229], v[200:201], v[100:101], v[228:229]
	v_fmac_f32_dpp v218, v100, v180 row_shr:1 row_mask:0xf bank_mask:0xf bound_ctrl:1
	v_fmac_f32_dpp v230, v116, v200 row_shl:1 row_mask:0xf bank_mask:0xf bound_ctrl:1
	v_fmac_f32_dpp v219, v101, v181 row_shr:1 row_mask:0xf bank_mask:0xf bound_ctrl:1
	v_fmac_f32_dpp v231, v117, v201 row_shl:1 row_mask:0xf bank_mask:0xf bound_ctrl:1
	v_pk_mul_f32 v[142:143], v[142:143], v[218:219]
	v_pk_mul_f32 v[178:179], v[178:179], v[252:253]
	v_pk_mul_f32 v[210:211], v[210:211], v[228:229]
	v_pk_mul_f32 v[212:213], v[212:213], v[230:231]
	v_cvt_pk_bf16_f32 v236, v142, v143
	v_cvt_pk_bf16_f32 v240, v178, v179
	v_cvt_pk_bf16_f32 v244, v210, v211
	v_cvt_pk_bf16_f32 v248, v212, v213
	v_pk_fma_f32 v[142:143], v[154:155], v[126:127], v[170:171]
	v_pk_fma_f32 v[178:179], v[154:155], v[70:71], v[170:171]
	v_pk_fma_f32 v[210:211], v[154:155], v[62:63], v[170:171]
	v_pk_fma_f32 v[212:213], v[154:155], v[110:111], v[170:171]
	v_pk_fma_f32 v[142:143], v[162:163], v[70:71], v[142:143]
	v_pk_fma_f32 v[178:179], v[146:147], v[126:127], v[178:179]
	v_pk_fma_f32 v[210:211], v[146:147], v[70:71], v[210:211]
	v_pk_fma_f32 v[212:213], v[146:147], v[62:63], v[212:213]
	v_pk_fma_f32 v[178:179], v[162:163], v[62:63], v[178:179]
	v_pk_fma_f32 v[210:211], v[162:163], v[110:111], v[210:211]
	v_fmac_f32_dpp v142, v110, v146 row_shr:1 row_mask:0xf bank_mask:0xf bound_ctrl:1
	v_fmac_f32_dpp v212, v126, v162 row_shl:1 row_mask:0xf bank_mask:0xf bound_ctrl:1
	v_fmac_f32_dpp v143, v111, v147 row_shr:1 row_mask:0xf bank_mask:0xf bound_ctrl:1
	v_fmac_f32_dpp v213, v127, v163 row_shl:1 row_mask:0xf bank_mask:0xf bound_ctrl:1
	v_pk_mul_f32 v[218:219], v[142:143], s[54:55] op_sel_hi:[1,0]
	v_pk_mul_f32 v[252:253], v[178:179], s[54:55] op_sel_hi:[1,0]
	v_pk_mul_f32 v[228:229], v[210:211], s[54:55] op_sel_hi:[1,0]
	v_pk_mul_f32 v[230:231], v[212:213], s[54:55] op_sel_hi:[1,0]
	v_exp_f32_e32 v218, v218
	v_exp_f32_e32 v219, v219
	v_exp_f32_e32 v252, v252
	v_exp_f32_e32 v253, v253
	v_exp_f32_e32 v228, v228
	v_exp_f32_e32 v229, v229
	v_exp_f32_e32 v230, v230
	v_exp_f32_e32 v231, v231
	v_pk_add_f32 v[218:219], v[218:219], s[56:57] op_sel_hi:[1,0]
	v_pk_add_f32 v[252:253], v[252:253], s[56:57] op_sel_hi:[1,0]
	v_pk_add_f32 v[228:229], v[228:229], s[56:57] op_sel_hi:[1,0]
	v_pk_add_f32 v[230:231], v[230:231], s[56:57] op_sel_hi:[1,0]
	v_rcp_f32_e32 v218, v218
	v_rcp_f32_e32 v219, v219
	v_rcp_f32_e32 v252, v252
	v_rcp_f32_e32 v253, v253
	v_rcp_f32_e32 v228, v228
	v_rcp_f32_e32 v229, v229
	v_rcp_f32_e32 v230, v230
	v_rcp_f32_e32 v231, v231
	v_pk_mul_f32 v[142:143], v[142:143], v[218:219]
	v_pk_mul_f32 v[178:179], v[178:179], v[252:253]
	v_pk_mul_f32 v[210:211], v[210:211], v[228:229]
	v_pk_mul_f32 v[212:213], v[212:213], v[230:231]
	v_pk_fma_f32 v[218:219], v[190:191], v[118:119], v[222:223]
	v_pk_fma_f32 v[252:253], v[190:191], v[54:55], v[222:223]
	v_pk_fma_f32 v[228:229], v[190:191], v[46:47], v[222:223]
	v_pk_fma_f32 v[230:231], v[190:191], v[102:103], v[222:223]
	v_pk_fma_f32 v[218:219], v[202:203], v[54:55], v[218:219]
	v_pk_fma_f32 v[252:253], v[182:183], v[118:119], v[252:253]
	v_pk_fma_f32 v[228:229], v[182:183], v[54:55], v[228:229]
	v_pk_fma_f32 v[230:231], v[182:183], v[46:47], v[230:231]
	v_pk_fma_f32 v[252:253], v[202:203], v[46:47], v[252:253]
	v_pk_fma_f32 v[228:229], v[202:203], v[102:103], v[228:229]
	v_fmac_f32_dpp v218, v102, v182 row_shr:1 row_mask:0xf bank_mask:0xf bound_ctrl:1
	v_fmac_f32_dpp v230, v118, v202 row_shl:1 row_mask:0xf bank_mask:0xf bound_ctrl:1
	v_fmac_f32_dpp v219, v103, v183 row_shr:1 row_mask:0xf bank_mask:0xf bound_ctrl:1
	v_fmac_f32_dpp v231, v119, v203 row_shl:1 row_mask:0xf bank_mask:0xf bound_ctrl:1
	v_pk_mul_f32 v[142:143], v[142:143], v[218:219]
	v_pk_mul_f32 v[178:179], v[178:179], v[252:253]
	v_pk_mul_f32 v[210:211], v[210:211], v[228:229]
	v_pk_mul_f32 v[212:213], v[212:213], v[230:231]
	v_cvt_pk_bf16_f32 v237, v142, v143
	v_cvt_pk_bf16_f32 v241, v178, v179
	v_cvt_pk_bf16_f32 v245, v210, v211
	v_cvt_pk_bf16_f32 v249, v212, v213
	s_waitcnt lgkmcnt(4)
; template <int CTRL> __device__ __forceinline__ float dppz(float v) { return __int_as_float(__builtin_amdgcn_update_dpp(0, __float_as_int(v), CTRL, 0xf, 0xf, true)); }
;     __device__ __forceinline__ void operator()(f32x4 (&acc)[2][2][4][2], const Unit& u, int wr, int wc, int fr, int fq, const LAS float* rtab) const {
;     ...
;                 for (int m = 0; m < 4; ++m) {
;                     float y[4];
; #pragma unroll
;                     for (int jj = 0; jj < 4; ++jj) {
;                         const float gc = acc[ai][0][m][n][jj], uc = acc[ai][1][m][n][jj];
;                         const float gb = m > 0 ? acc[ai][0][m - 1][n][jj] : 0.f, ga = m < 3 ? acc[ai][0][m + 1][n][jj] : 0.f;
;                         const float ub = m > 0 ? acc[ai][1][m - 1][n][jj] : 0.f, ua = m < 3 ? acc[ai][1][m + 1][n][jj] : 0.f;
;                         const float gp = dppz<0x111>(gc) + dppz<0x10F>(gb), gn = dppz<0x101>(gc) + dppz<0x11F>(ga);
;                         const float up = dppz<0x111>(uc) + dppz<0x10F>(ub), un = dppz<0x101>(uc) + dppz<0x11F>(ua);
;                         const float hg = wg0[jj] * gp + wg1[jj] * gc + wg2[jj] * gn + bg[jj];
;                         const float hu = wu0[jj] * up + wu1[jj] * uc + wu2[jj] * un + bu[jj];
;                         const float sg = __builtin_amdgcn_rcpf(1.f + __builtin_amdgcn_exp2f(-1.4426950408889634f * hg));
;                         y[jj] = hg * sg * hu; }
	v_pk_fma_f32 v[142:143], v[156:157], v[120:121], v[172:173]
	v_pk_fma_f32 v[178:179], v[156:157], v[64:65], v[172:173]
	v_pk_fma_f32 v[210:211], v[156:157], v[20:21], v[172:173]
	v_pk_fma_f32 v[212:213], v[156:157], v[104:105], v[172:173]
	v_pk_fma_f32 v[142:143], v[164:165], v[64:65], v[142:143]
	v_pk_fma_f32 v[178:179], v[148:149], v[120:121], v[178:179]
	v_pk_fma_f32 v[210:211], v[148:149], v[64:65], v[210:211]
	v_pk_fma_f32 v[212:213], v[148:149], v[20:21], v[212:213]
	v_pk_fma_f32 v[178:179], v[164:165], v[20:21], v[178:179]
	v_pk_fma_f32 v[210:211], v[164:165], v[104:105], v[210:211]
	v_fmac_f32_dpp v142, v104, v148 row_shr:1 row_mask:0xf bank_mask:0xf bound_ctrl:1
	v_fmac_f32_dpp v212, v120, v164 row_shl:1 row_mask:0xf bank_mask:0xf bound_ctrl:1
	v_fmac_f32_dpp v143, v105, v149 row_shr:1 row_mask:0xf bank_mask:0xf bound_ctrl:1
	v_fmac_f32_dpp v213, v121, v165 row_shl:1 row_mask:0xf bank_mask:0xf bound_ctrl:1
	v_pk_mul_f32 v[218:219], v[142:143], s[54:55] op_sel_hi:[1,0]
	v_pk_mul_f32 v[252:253], v[178:179], s[54:55] op_sel_hi:[1,0]
	v_pk_mul_f32 v[228:229], v[210:211], s[54:55] op_sel_hi:[1,0]
	v_pk_mul_f32 v[230:231], v[212:213], s[54:55] op_sel_hi:[1,0]
	v_exp_f32_e32 v218, v218
	v_exp_f32_e32 v219, v219
	v_exp_f32_e32 v252, v252
	v_exp_f32_e32 v253, v253
	v_exp_f32_e32 v228, v228
	v_exp_f32_e32 v229, v229
	v_exp_f32_e32 v230, v230
	v_exp_f32_e32 v231, v231
	v_pk_add_f32 v[218:219], v[218:219], s[56:57] op_sel_hi:[1,0]
	v_pk_add_f32 v[252:253], v[252:253], s[56:57] op_sel_hi:[1,0]
	v_pk_add_f32 v[228:229], v[228:229], s[56:57] op_sel_hi:[1,0]
	v_pk_add_f32 v[230:231], v[230:231], s[56:57] op_sel_hi:[1,0]
	v_rcp_f32_e32 v218, v218
	v_rcp_f32_e32 v219, v219
	v_rcp_f32_e32 v252, v252
	v_rcp_f32_e32 v253, v253
	v_rcp_f32_e32 v228, v228
	v_rcp_f32_e32 v229, v229
	v_rcp_f32_e32 v230, v230
	v_rcp_f32_e32 v231, v231
	v_pk_mul_f32 v[142:143], v[142:143], v[218:219]
	v_pk_mul_f32 v[178:179], v[178:179], v[252:253]
	v_pk_mul_f32 v[210:211], v[210:211], v[228:229]
	v_pk_mul_f32 v[212:213], v[212:213], v[230:231]
	s_waitcnt lgkmcnt(0)
	v_pk_fma_f32 v[218:219], v[196:197], v[112:113], v[224:225]
	v_pk_fma_f32 v[252:253], v[196:197], v[48:49], v[224:225]
	v_pk_fma_f32 v[228:229], v[196:197], v[16:17], v[224:225]
	v_pk_fma_f32 v[230:231], v[196:197], v[96:97], v[224:225]
	v_pk_fma_f32 v[218:219], v[204:205], v[48:49], v[218:219]
	v_pk_fma_f32 v[252:253], v[184:185], v[112:113], v[252:253]
	v_pk_fma_f32 v[228:229], v[184:185], v[48:49], v[228:229]
	v_pk_fma_f32 v[230:231], v[184:185], v[16:17], v[230:231]
	v_pk_fma_f32 v[252:253], v[204:205], v[16:17], v[252:253]
	v_pk_fma_f32 v[228:229], v[204:205], v[96:97], v[228:229]
	v_fmac_f32_dpp v218, v96, v184 row_shr:1 row_mask:0xf bank_mask:0xf bound_ctrl:1
	v_fmac_f32_dpp v230, v112, v204 row_shl:1 row_mask:0xf bank_mask:0xf bound_ctrl:1
	v_fmac_f32_dpp v219, v97, v185 row_shr:1 row_mask:0xf bank_mask:0xf bound_ctrl:1
	v_fmac_f32_dpp v231, v113, v205 row_shl:1 row_mask:0xf bank_mask:0xf bound_ctrl:1
	v_pk_mul_f32 v[142:143], v[142:143], v[218:219]
	v_pk_mul_f32 v[178:179], v[178:179], v[252:253]
	v_pk_mul_f32 v[210:211], v[210:211], v[228:229]
	v_pk_mul_f32 v[212:213], v[212:213], v[230:231]
	v_cvt_pk_bf16_f32 v238, v142, v143
	v_cvt_pk_bf16_f32 v242, v178, v179
	v_cvt_pk_bf16_f32 v246, v210, v211
	v_cvt_pk_bf16_f32 v250, v212, v213
	v_pk_fma_f32 v[142:143], v[158:159], v[122:123], v[174:175]
	v_pk_fma_f32 v[178:179], v[158:159], v[66:67], v[174:175]
	v_pk_fma_f32 v[210:211], v[158:159], v[22:23], v[174:175]
	v_pk_fma_f32 v[212:213], v[158:159], v[106:107], v[174:175]
	v_pk_fma_f32 v[142:143], v[166:167], v[66:67], v[142:143]
	v_pk_fma_f32 v[178:179], v[150:151], v[122:123], v[178:179]
	v_pk_fma_f32 v[210:211], v[150:151], v[66:67], v[210:211]
	v_pk_fma_f32 v[212:213], v[150:151], v[22:23], v[212:213]
	v_pk_fma_f32 v[178:179], v[166:167], v[22:23], v[178:179]
	v_pk_fma_f32 v[210:211], v[166:167], v[106:107], v[210:211]
	v_fmac_f32_dpp v142, v106, v150 row_shr:1 row_mask:0xf bank_mask:0xf bound_ctrl:1
	v_fmac_f32_dpp v212, v122, v166 row_shl:1 row_mask:0xf bank_mask:0xf bound_ctrl:1
	v_fmac_f32_dpp v143, v107, v151 row_shr:1 row_mask:0xf bank_mask:0xf bound_ctrl:1
	v_fmac_f32_dpp v213, v123, v167 row_shl:1 row_mask:0xf bank_mask:0xf bound_ctrl:1
	v_pk_mul_f32 v[218:219], v[142:143], s[54:55] op_sel_hi:[1,0]
	v_pk_mul_f32 v[252:253], v[178:179], s[54:55] op_sel_hi:[1,0]
	v_pk_mul_f32 v[228:229], v[210:211], s[54:55] op_sel_hi:[1,0]
	v_pk_mul_f32 v[230:231], v[212:213], s[54:55] op_sel_hi:[1,0]
	v_exp_f32_e32 v218, v218
	v_exp_f32_e32 v219, v219
	v_exp_f32_e32 v252, v252
	v_exp_f32_e32 v253, v253
	v_exp_f32_e32 v228, v228
	v_exp_f32_e32 v229, v229
	v_exp_f32_e32 v230, v230
	v_exp_f32_e32 v231, v231
	v_pk_add_f32 v[218:219], v[218:219], s[56:57] op_sel_hi:[1,0]
	v_pk_add_f32 v[252:253], v[252:253], s[56:57] op_sel_hi:[1,0]
	v_pk_add_f32 v[228:229], v[228:229], s[56:57] op_sel_hi:[1,0]
	v_pk_add_f32 v[230:231], v[230:231], s[56:57] op_sel_hi:[1,0]
	v_rcp_f32_e32 v218, v218
	v_rcp_f32_e32 v219, v219
	v_rcp_f32_e32 v252, v252
	v_rcp_f32_e32 v253, v253
	v_rcp_f32_e32 v228, v228
	v_rcp_f32_e32 v229, v229
	v_rcp_f32_e32 v230, v230
	v_rcp_f32_e32 v231, v231
	v_pk_mul_f32 v[142:143], v[142:143], v[218:219]
	v_pk_mul_f32 v[178:179], v[178:179], v[252:253]
	v_pk_mul_f32 v[210:211], v[210:211], v[228:229]
	v_pk_mul_f32 v[212:213], v[212:213], v[230:231]
	v_pk_fma_f32 v[218:219], v[198:199], v[114:115], v[226:227]
	v_pk_fma_f32 v[252:253], v[198:199], v[50:51], v[226:227]
	v_pk_fma_f32 v[228:229], v[198:199], v[18:19], v[226:227]
	v_pk_fma_f32 v[230:231], v[198:199], v[98:99], v[226:227]
; __device__ __forceinline__ unsigned cvt_pk_bf16(float lo, float hi) { unsigned r; asm volatile("v_cvt_pk_bf16_f32 %0, %1, %2" : "=v"(r) : "v"(lo), "v"(hi)); return r; }
; template <int CTRL> __device__ __forceinline__ float dppz(float v) { return __int_as_float(__builtin_amdgcn_update_dpp(0, __float_as_int(v), CTRL, 0xf, 0xf, true)); }
;     __device__ __forceinline__ void operator()(f32x4 (&acc)[2][2][4][2], const Unit& u, int wr, int wc, int fr, int fq, const LAS float* rtab) const {
;     ...
;                 for (int m = 0; m < 4; ++m) {
;                     float y[4];
; #pragma unroll
;                     for (int jj = 0; jj < 4; ++jj) {
;                         const float gc = acc[ai][0][m][n][jj], uc = acc[ai][1][m][n][jj];
;                         const float gb = m > 0 ? acc[ai][0][m - 1][n][jj] : 0.f, ga = m < 3 ? acc[ai][0][m + 1][n][jj] : 0.f;
;                         const float ub = m > 0 ? acc[ai][1][m - 1][n][jj] : 0.f, ua = m < 3 ? acc[ai][1][m + 1][n][jj] : 0.f;
;                         const float gp = dppz<0x111>(gc) + dppz<0x10F>(gb), gn = dppz<0x101>(gc) + dppz<0x11F>(ga);
;                         const float up = dppz<0x111>(uc) + dppz<0x10F>(ub), un = dppz<0x101>(uc) + dppz<0x11F>(ua);
;                         const float hg = wg0[jj] * gp + wg1[jj] * gc + wg2[jj] * gn + bg[jj];
;                         const float hu = wu0[jj] * up + wu1[jj] * uc + wu2[jj] * un + bu[jj];
;                         const float sg = __builtin_amdgcn_rcpf(1.f + __builtin_amdgcn_exp2f(-1.4426950408889634f * hg));
;                         y[jj] = hg * sg * hu; }
;                     u32x2 pk; pk.x = cvt_pk_bf16(y[0], y[1]); pk.y = cvt_pk_bf16(y[2], y[3]);
;                     if (n == 0) ypk[ai][m] = pk;
;                     else {
;                         const bool deferred = (m == 0 && fr == 0) || (m == 3 && fr == 15);
;                         if (!deferred) { u32x4 w; w.x = ypk[ai][m].x; w.y = ypk[ai][m].y; w.z = pk.x; w.w = pk.y; *(u32x4*)(act + (size_t)(r64 + m * 16 + fr) * DFF + c0) = w; } }
	v_pk_fma_f32 v[218:219], v[206:207], v[50:51], v[218:219]
	v_pk_fma_f32 v[252:253], v[186:187], v[114:115], v[252:253]
	v_pk_fma_f32 v[228:229], v[186:187], v[50:51], v[228:229]
	v_pk_fma_f32 v[230:231], v[186:187], v[18:19], v[230:231]
	v_pk_fma_f32 v[252:253], v[206:207], v[18:19], v[252:253]
	v_pk_fma_f32 v[228:229], v[206:207], v[98:99], v[228:229]
	v_fmac_f32_dpp v218, v98, v186 row_shr:1 row_mask:0xf bank_mask:0xf bound_ctrl:1
	v_fmac_f32_dpp v230, v114, v206 row_shl:1 row_mask:0xf bank_mask:0xf bound_ctrl:1
	v_fmac_f32_dpp v219, v99, v187 row_shr:1 row_mask:0xf bank_mask:0xf bound_ctrl:1
	v_fmac_f32_dpp v231, v115, v207 row_shl:1 row_mask:0xf bank_mask:0xf bound_ctrl:1
	v_pk_mul_f32 v[142:143], v[142:143], v[218:219]
	v_pk_mul_f32 v[178:179], v[178:179], v[252:253]
	v_pk_mul_f32 v[210:211], v[210:211], v[228:229]
	v_pk_mul_f32 v[212:213], v[212:213], v[230:231]
	v_cvt_pk_bf16_f32 v239, v142, v143
	v_cvt_pk_bf16_f32 v243, v178, v179
	v_cvt_pk_bf16_f32 v247, v210, v211
	v_cvt_pk_bf16_f32 v251, v212, v213
	s_mov_b64 s[58:59], s[28:29]
	s_mov_b64 exec, s[12:13]
	global_store_dwordx4 v234, v[236:239], s[58:59]
	s_mov_b64 exec, -1
	s_add_u32 s58, s28, 0x2c00
	s_addc_u32 s59, s29, 0
	global_store_dwordx4 v234, v[240:243], s[58:59]
	s_add_u32 s58, s28, 0x5800
	s_addc_u32 s59, s29, 0
	global_store_dwordx4 v234, v[244:247], s[58:59]
	s_add_u32 s58, s28, 0x8400
	s_addc_u32 s59, s29, 0
	s_mov_b64 exec, s[10:11]
	global_store_dwordx4 v234, v[248:251], s[58:59]
	s_mov_b64 exec, -1
	v_pk_fma_f32 v[142:143], v[152:153], v[92:93], v[168:169]
	v_pk_fma_f32 v[178:179], v[152:153], v[36:37], v[168:169]
	v_pk_fma_f32 v[210:211], v[152:153], v[32:33], v[168:169]
	v_pk_fma_f32 v[212:213], v[152:153], v[76:77], v[168:169]
	v_pk_fma_f32 v[142:143], v[160:161], v[36:37], v[142:143]
	v_pk_fma_f32 v[178:179], v[144:145], v[92:93], v[178:179]
	v_pk_fma_f32 v[210:211], v[144:145], v[36:37], v[210:211]
	v_pk_fma_f32 v[212:213], v[144:145], v[32:33], v[212:213]
	v_pk_fma_f32 v[178:179], v[160:161], v[32:33], v[178:179]
	v_pk_fma_f32 v[210:211], v[160:161], v[76:77], v[210:211]
	v_fmac_f32_dpp v142, v76, v144 row_shr:1 row_mask:0xf bank_mask:0xf bound_ctrl:1
	v_fmac_f32_dpp v212, v92, v160 row_shl:1 row_mask:0xf bank_mask:0xf bound_ctrl:1
	v_fmac_f32_dpp v143, v77, v145 row_shr:1 row_mask:0xf bank_mask:0xf bound_ctrl:1
	v_fmac_f32_dpp v213, v93, v161 row_shl:1 row_mask:0xf bank_mask:0xf bound_ctrl:1
	v_pk_mul_f32 v[218:219], v[142:143], s[54:55] op_sel_hi:[1,0]
	v_pk_mul_f32 v[252:253], v[178:179], s[54:55] op_sel_hi:[1,0]
	v_pk_mul_f32 v[228:229], v[210:211], s[54:55] op_sel_hi:[1,0]
	v_pk_mul_f32 v[230:231], v[212:213], s[54:55] op_sel_hi:[1,0]
	v_exp_f32_e32 v218, v218
	v_exp_f32_e32 v219, v219
	v_exp_f32_e32 v252, v252
	v_exp_f32_e32 v253, v253
	v_exp_f32_e32 v228, v228
	v_exp_f32_e32 v229, v229
	v_exp_f32_e32 v230, v230
	v_exp_f32_e32 v231, v231
	v_pk_add_f32 v[218:219], v[218:219], s[56:57] op_sel_hi:[1,0]
	v_pk_add_f32 v[252:253], v[252:253], s[56:57] op_sel_hi:[1,0]
	v_pk_add_f32 v[228:229], v[228:229], s[56:57] op_sel_hi:[1,0]
	v_pk_add_f32 v[230:231], v[230:231], s[56:57] op_sel_hi:[1,0]
	v_rcp_f32_e32 v218, v218
	v_rcp_f32_e32 v219, v219
	v_rcp_f32_e32 v252, v252
	v_rcp_f32_e32 v253, v253
	v_rcp_f32_e32 v228, v228
	v_rcp_f32_e32 v229, v229
	v_rcp_f32_e32 v230, v230
	v_rcp_f32_e32 v231, v231
	v_pk_mul_f32 v[142:143], v[142:143], v[218:219]
	v_pk_mul_f32 v[178:179], v[178:179], v[252:253]
	v_pk_mul_f32 v[210:211], v[210:211], v[228:229]
	v_pk_mul_f32 v[212:213], v[212:213], v[230:231]
	v_pk_fma_f32 v[218:219], v[188:189], v[84:85], v[220:221]
	v_pk_fma_f32 v[252:253], v[188:189], v[28:29], v[220:221]
	v_pk_fma_f32 v[228:229], v[188:189], v[24:25], v[220:221]
	v_pk_fma_f32 v[230:231], v[188:189], v[72:73], v[220:221]
	v_pk_fma_f32 v[218:219], v[200:201], v[28:29], v[218:219]
	v_pk_fma_f32 v[252:253], v[180:181], v[84:85], v[252:253]
	v_pk_fma_f32 v[228:229], v[180:181], v[28:29], v[228:229]
	v_pk_fma_f32 v[230:231], v[180:181], v[24:25], v[230:231]
	v_pk_fma_f32 v[252:253], v[200:201], v[24:25], v[252:253]
	v_pk_fma_f32 v[228:229], v[200:201], v[72:73], v[228:229]
	v_fmac_f32_dpp v218, v72, v180 row_shr:1 row_mask:0xf bank_mask:0xf bound_ctrl:1
	v_fmac_f32_dpp v230, v84, v200 row_shl:1 row_mask:0xf bank_mask:0xf bound_ctrl:1
	v_fmac_f32_dpp v219, v73, v181 row_shr:1 row_mask:0xf bank_mask:0xf bound_ctrl:1
	v_fmac_f32_dpp v231, v85, v201 row_shl:1 row_mask:0xf bank_mask:0xf bound_ctrl:1
	v_pk_mul_f32 v[142:143], v[142:143], v[218:219]
	v_pk_mul_f32 v[178:179], v[178:179], v[252:253]
	v_pk_mul_f32 v[210:211], v[210:211], v[228:229]
	v_pk_mul_f32 v[212:213], v[212:213], v[230:231]
	v_cvt_pk_bf16_f32 v236, v142, v143
	v_cvt_pk_bf16_f32 v240, v178, v179
	v_cvt_pk_bf16_f32 v244, v210, v211
	v_cvt_pk_bf16_f32 v248, v212, v213
	v_pk_fma_f32 v[142:143], v[154:155], v[94:95], v[170:171]
	v_pk_fma_f32 v[178:179], v[154:155], v[38:39], v[170:171]
	v_pk_fma_f32 v[210:211], v[154:155], v[34:35], v[170:171]
	v_pk_fma_f32 v[212:213], v[154:155], v[78:79], v[170:171]
	v_pk_fma_f32 v[142:143], v[162:163], v[38:39], v[142:143]
	v_pk_fma_f32 v[178:179], v[146:147], v[94:95], v[178:179]
	v_pk_fma_f32 v[210:211], v[146:147], v[38:39], v[210:211]
	v_pk_fma_f32 v[212:213], v[146:147], v[34:35], v[212:213]
	v_pk_fma_f32 v[178:179], v[162:163], v[34:35], v[178:179]
	v_pk_fma_f32 v[210:211], v[162:163], v[78:79], v[210:211]
	v_fmac_f32_dpp v142, v78, v146 row_shr:1 row_mask:0xf bank_mask:0xf bound_ctrl:1
	v_fmac_f32_dpp v212, v94, v162 row_shl:1 row_mask:0xf bank_mask:0xf bound_ctrl:1
	v_fmac_f32_dpp v143, v79, v147 row_shr:1 row_mask:0xf bank_mask:0xf bound_ctrl:1
; __device__ __forceinline__ unsigned cvt_pk_bf16(float lo, float hi) { unsigned r; asm volatile("v_cvt_pk_bf16_f32 %0, %1, %2" : "=v"(r) : "v"(lo), "v"(hi)); return r; }
; template <int CTRL> __device__ __forceinline__ float dppz(float v) { return __int_as_float(__builtin_amdgcn_update_dpp(0, __float_as_int(v), CTRL, 0xf, 0xf, true)); }
;     __device__ __forceinline__ void operator()(f32x4 (&acc)[2][2][4][2], const Unit& u, int wr, int wc, int fr, int fq, const LAS float* rtab) const {
;     ...
;                 for (int m = 0; m < 4; ++m) {
;                     float y[4];
; #pragma unroll
;                     for (int jj = 0; jj < 4; ++jj) {
;                         const float gc = acc[ai][0][m][n][jj], uc = acc[ai][1][m][n][jj];
;                         const float gb = m > 0 ? acc[ai][0][m - 1][n][jj] : 0.f, ga = m < 3 ? acc[ai][0][m + 1][n][jj] : 0.f;
;                         const float ub = m > 0 ? acc[ai][1][m - 1][n][jj] : 0.f, ua = m < 3 ? acc[ai][1][m + 1][n][jj] : 0.f;
;                         const float gp = dppz<0x111>(gc) + dppz<0x10F>(gb), gn = dppz<0x101>(gc) + dppz<0x11F>(ga);
;                         const float up = dppz<0x111>(uc) + dppz<0x10F>(ub), un = dppz<0x101>(uc) + dppz<0x11F>(ua);
;                         const float hg = wg0[jj] * gp + wg1[jj] * gc + wg2[jj] * gn + bg[jj];
;                         const float hu = wu0[jj] * up + wu1[jj] * uc + wu2[jj] * un + bu[jj];
;                         const float sg = __builtin_amdgcn_rcpf(1.f + __builtin_amdgcn_exp2f(-1.4426950408889634f * hg));
;                         y[jj] = hg * sg * hu; }
;                     u32x2 pk; pk.x = cvt_pk_bf16(y[0], y[1]); pk.y = cvt_pk_bf16(y[2], y[3]);
;                     if (n == 0) ypk[ai][m] = pk;
;                     else {
;                         const bool deferred = (m == 0 && fr == 0) || (m == 3 && fr == 15);
;                         if (!deferred) { u32x4 w; w.x = ypk[ai][m].x; w.y = ypk[ai][m].y; w.z = pk.x; w.w = pk.y; *(u32x4*)(act + (size_t)(r64 + m * 16 + fr) * DFF + c0) = w; } }
	v_fmac_f32_dpp v213, v95, v163 row_shl:1 row_mask:0xf bank_mask:0xf bound_ctrl:1
	v_pk_mul_f32 v[218:219], v[142:143], s[54:55] op_sel_hi:[1,0]
	v_pk_mul_f32 v[252:253], v[178:179], s[54:55] op_sel_hi:[1,0]
	v_pk_mul_f32 v[228:229], v[210:211], s[54:55] op_sel_hi:[1,0]
	v_pk_mul_f32 v[230:231], v[212:213], s[54:55] op_sel_hi:[1,0]
	v_exp_f32_e32 v218, v218
	v_exp_f32_e32 v219, v219
	v_exp_f32_e32 v252, v252
	v_exp_f32_e32 v253, v253
	v_exp_f32_e32 v228, v228
	v_exp_f32_e32 v229, v229
	v_exp_f32_e32 v230, v230
	v_exp_f32_e32 v231, v231
	v_pk_add_f32 v[218:219], v[218:219], s[56:57] op_sel_hi:[1,0]
	v_pk_add_f32 v[252:253], v[252:253], s[56:57] op_sel_hi:[1,0]
	v_pk_add_f32 v[228:229], v[228:229], s[56:57] op_sel_hi:[1,0]
	v_pk_add_f32 v[230:231], v[230:231], s[56:57] op_sel_hi:[1,0]
	v_rcp_f32_e32 v218, v218
	v_rcp_f32_e32 v219, v219
	v_rcp_f32_e32 v252, v252
	v_rcp_f32_e32 v253, v253
	v_rcp_f32_e32 v228, v228
	v_rcp_f32_e32 v229, v229
	v_rcp_f32_e32 v230, v230
	v_rcp_f32_e32 v231, v231
	v_pk_mul_f32 v[142:143], v[142:143], v[218:219]
	v_pk_mul_f32 v[178:179], v[178:179], v[252:253]
	v_pk_mul_f32 v[210:211], v[210:211], v[228:229]
	v_pk_mul_f32 v[212:213], v[212:213], v[230:231]
	v_pk_fma_f32 v[218:219], v[190:191], v[86:87], v[222:223]
	v_pk_fma_f32 v[252:253], v[190:191], v[30:31], v[222:223]
	v_pk_fma_f32 v[228:229], v[190:191], v[26:27], v[222:223]
	v_pk_fma_f32 v[230:231], v[190:191], v[74:75], v[222:223]
	v_pk_fma_f32 v[218:219], v[202:203], v[30:31], v[218:219]
	v_pk_fma_f32 v[252:253], v[182:183], v[86:87], v[252:253]
	v_pk_fma_f32 v[228:229], v[182:183], v[30:31], v[228:229]
	v_pk_fma_f32 v[230:231], v[182:183], v[26:27], v[230:231]
	v_pk_fma_f32 v[252:253], v[202:203], v[26:27], v[252:253]
	v_pk_fma_f32 v[228:229], v[202:203], v[74:75], v[228:229]
	v_fmac_f32_dpp v218, v74, v182 row_shr:1 row_mask:0xf bank_mask:0xf bound_ctrl:1
	v_fmac_f32_dpp v230, v86, v202 row_shl:1 row_mask:0xf bank_mask:0xf bound_ctrl:1
	v_fmac_f32_dpp v219, v75, v183 row_shr:1 row_mask:0xf bank_mask:0xf bound_ctrl:1
	v_fmac_f32_dpp v231, v87, v203 row_shl:1 row_mask:0xf bank_mask:0xf bound_ctrl:1
	v_pk_mul_f32 v[142:143], v[142:143], v[218:219]
	v_pk_mul_f32 v[178:179], v[178:179], v[252:253]
	v_pk_mul_f32 v[210:211], v[210:211], v[228:229]
	v_pk_mul_f32 v[212:213], v[212:213], v[230:231]
	v_cvt_pk_bf16_f32 v237, v142, v143
	v_cvt_pk_bf16_f32 v241, v178, v179
	v_cvt_pk_bf16_f32 v245, v210, v211
	v_cvt_pk_bf16_f32 v249, v212, v213
	v_pk_fma_f32 v[142:143], v[156:157], v[88:89], v[172:173]
	v_pk_fma_f32 v[178:179], v[156:157], v[12:13], v[172:173]
	v_pk_fma_f32 v[210:211], v[156:157], v[4:5], v[172:173]
	v_pk_fma_f32 v[212:213], v[156:157], v[56:57], v[172:173]
	v_pk_fma_f32 v[142:143], v[164:165], v[12:13], v[142:143]
	v_pk_fma_f32 v[178:179], v[148:149], v[88:89], v[178:179]
	v_pk_fma_f32 v[210:211], v[148:149], v[12:13], v[210:211]
	v_pk_fma_f32 v[212:213], v[148:149], v[4:5], v[212:213]
	v_pk_fma_f32 v[178:179], v[164:165], v[4:5], v[178:179]
	v_pk_fma_f32 v[210:211], v[164:165], v[56:57], v[210:211]
	v_fmac_f32_dpp v142, v56, v148 row_shr:1 row_mask:0xf bank_mask:0xf bound_ctrl:1
	v_fmac_f32_dpp v212, v88, v164 row_shl:1 row_mask:0xf bank_mask:0xf bound_ctrl:1
	v_fmac_f32_dpp v143, v57, v149 row_shr:1 row_mask:0xf bank_mask:0xf bound_ctrl:1
	v_fmac_f32_dpp v213, v89, v165 row_shl:1 row_mask:0xf bank_mask:0xf bound_ctrl:1
	v_pk_mul_f32 v[218:219], v[142:143], s[54:55] op_sel_hi:[1,0]
	v_pk_mul_f32 v[252:253], v[178:179], s[54:55] op_sel_hi:[1,0]
	v_pk_mul_f32 v[228:229], v[210:211], s[54:55] op_sel_hi:[1,0]
	v_pk_mul_f32 v[230:231], v[212:213], s[54:55] op_sel_hi:[1,0]
	v_exp_f32_e32 v218, v218
	v_exp_f32_e32 v219, v219
	v_exp_f32_e32 v252, v252
	v_exp_f32_e32 v253, v253
	v_exp_f32_e32 v228, v228
	v_exp_f32_e32 v229, v229
	v_exp_f32_e32 v230, v230
	v_exp_f32_e32 v231, v231
	v_pk_add_f32 v[218:219], v[218:219], s[56:57] op_sel_hi:[1,0]
	v_pk_add_f32 v[252:253], v[252:253], s[56:57] op_sel_hi:[1,0]
	v_pk_add_f32 v[228:229], v[228:229], s[56:57] op_sel_hi:[1,0]
	v_pk_add_f32 v[230:231], v[230:231], s[56:57] op_sel_hi:[1,0]
	v_rcp_f32_e32 v218, v218
	v_rcp_f32_e32 v219, v219
	v_rcp_f32_e32 v252, v252
	v_rcp_f32_e32 v253, v253
	v_rcp_f32_e32 v228, v228
	v_rcp_f32_e32 v229, v229
	v_rcp_f32_e32 v230, v230
	v_rcp_f32_e32 v231, v231
	v_pk_mul_f32 v[142:143], v[142:143], v[218:219]
	v_pk_mul_f32 v[178:179], v[178:179], v[252:253]
	v_pk_mul_f32 v[210:211], v[210:211], v[228:229]
	v_pk_mul_f32 v[212:213], v[212:213], v[230:231]
	v_pk_fma_f32 v[218:219], v[196:197], v[80:81], v[224:225]
	v_pk_fma_f32 v[252:253], v[196:197], v[8:9], v[224:225]
	v_pk_fma_f32 v[228:229], v[196:197], v[0:1], v[224:225]
	v_pk_fma_f32 v[230:231], v[196:197], v[40:41], v[224:225]
	v_pk_fma_f32 v[218:219], v[204:205], v[8:9], v[218:219]
;     __device__ __forceinline__ void operator()(f32x4 (&acc)[2][2][4][2], const Unit& u, int wr, int wc, int fr, int fq, const LAS float* rtab) const {
;     ...
;                 for (int m = 0; m < 4; ++m) {
;                     float y[4];
; #pragma unroll
;                     for (int jj = 0; jj < 4; ++jj) {
;                         const float gc = acc[ai][0][m][n][jj], uc = acc[ai][1][m][n][jj];
;                         const float gb = m > 0 ? acc[ai][0][m - 1][n][jj] : 0.f, ga = m < 3 ? acc[ai][0][m + 1][n][jj] : 0.f;
;                         const float ub = m > 0 ? acc[ai][1][m - 1][n][jj] : 0.f, ua = m < 3 ? acc[ai][1][m + 1][n][jj] : 0.f;
;                         const float gp = dppz<0x111>(gc) + dppz<0x10F>(gb), gn = dppz<0x101>(gc) + dppz<0x11F>(ga);
;                         const float up = dppz<0x111>(uc) + dppz<0x10F>(ub), un = dppz<0x101>(uc) + dppz<0x11F>(ua);
;                         const float hg = wg0[jj] * gp + wg1[jj] * gc + wg2[jj] * gn + bg[jj];
;                         const float hu = wu0[jj] * up + wu1[jj] * uc + wu2[jj] * un + bu[jj];
;                         const float sg = __builtin_amdgcn_rcpf(1.f + __builtin_amdgcn_exp2f(-1.4426950408889634f * hg));
;                         y[jj] = hg * sg * hu; }
;                     u32x2 pk; pk.x = cvt_pk_bf16(y[0], y[1]); pk.y = cvt_pk_bf16(y[2], y[3]);
;                     if (n == 0) ypk[ai][m] = pk;
;                     else {
;                         const bool deferred = (m == 0 && fr == 0) || (m == 3 && fr == 15);
;                         if (!deferred) { u32x4 w; w.x = ypk[ai][m].x; w.y = ypk[ai][m].y; w.z = pk.x; w.w = pk.y; *(u32x4*)(act + (size_t)(r64 + m * 16 + fr) * DFF + c0) = w; } }
; template <class Epi, bool KREV = false>
; __device__ __forceinline__ void gemm_phase(LAS unsigned char* lds, const Gemm g, const StaticOrder& S, const Epi& E, int wave_s) {
;     ...
;         if (!has_next) break;
; #pragma unroll
;         for (int a = 0; a < 2; ++a)
; #pragma unroll
;             for (int b = 0; b < 2; ++b)
; #pragma unroll
;                 for (int m = 0; m < 4; ++m)
; #pragma unroll
;                     for (int n = 0; n < 2; ++n) acc[a][b][m][n] = (f32x4){0.f, 0.f, 0.f, 0.f};
;         cur = nxt; cA = nA; cB = nB; ++ui;
	v_pk_fma_f32 v[252:253], v[184:185], v[80:81], v[252:253]
	v_pk_fma_f32 v[228:229], v[184:185], v[8:9], v[228:229]
	v_pk_fma_f32 v[230:231], v[184:185], v[0:1], v[230:231]
	v_pk_fma_f32 v[252:253], v[204:205], v[0:1], v[252:253]
	v_pk_fma_f32 v[228:229], v[204:205], v[40:41], v[228:229]
	v_fmac_f32_dpp v218, v40, v184 row_shr:1 row_mask:0xf bank_mask:0xf bound_ctrl:1
	v_fmac_f32_dpp v230, v80, v204 row_shl:1 row_mask:0xf bank_mask:0xf bound_ctrl:1
	v_fmac_f32_dpp v219, v41, v185 row_shr:1 row_mask:0xf bank_mask:0xf bound_ctrl:1
	v_fmac_f32_dpp v231, v81, v205 row_shl:1 row_mask:0xf bank_mask:0xf bound_ctrl:1
	v_pk_mul_f32 v[142:143], v[142:143], v[218:219]
	v_pk_mul_f32 v[178:179], v[178:179], v[252:253]
	v_pk_mul_f32 v[210:211], v[210:211], v[228:229]
	v_pk_mul_f32 v[212:213], v[212:213], v[230:231]
	v_cvt_pk_bf16_f32 v238, v142, v143
	v_cvt_pk_bf16_f32 v242, v178, v179
	v_cvt_pk_bf16_f32 v246, v210, v211
	v_cvt_pk_bf16_f32 v250, v212, v213
	v_pk_fma_f32 v[142:143], v[158:159], v[90:91], v[174:175]
	v_pk_fma_f32 v[178:179], v[158:159], v[14:15], v[174:175]
	v_pk_fma_f32 v[210:211], v[158:159], v[6:7], v[174:175]
	v_pk_fma_f32 v[212:213], v[158:159], v[58:59], v[174:175]
	v_pk_fma_f32 v[142:143], v[166:167], v[14:15], v[142:143]
	v_pk_fma_f32 v[178:179], v[150:151], v[90:91], v[178:179]
	v_pk_fma_f32 v[210:211], v[150:151], v[14:15], v[210:211]
	v_pk_fma_f32 v[212:213], v[150:151], v[6:7], v[212:213]
	v_pk_fma_f32 v[178:179], v[166:167], v[6:7], v[178:179]
	v_pk_fma_f32 v[210:211], v[166:167], v[58:59], v[210:211]
	v_fmac_f32_dpp v142, v58, v150 row_shr:1 row_mask:0xf bank_mask:0xf bound_ctrl:1
	v_fmac_f32_dpp v212, v90, v166 row_shl:1 row_mask:0xf bank_mask:0xf bound_ctrl:1
	v_fmac_f32_dpp v143, v59, v151 row_shr:1 row_mask:0xf bank_mask:0xf bound_ctrl:1
	v_fmac_f32_dpp v213, v91, v167 row_shl:1 row_mask:0xf bank_mask:0xf bound_ctrl:1
	v_pk_mul_f32 v[218:219], v[142:143], s[54:55] op_sel_hi:[1,0]
	v_pk_mul_f32 v[252:253], v[178:179], s[54:55] op_sel_hi:[1,0]
	v_pk_mul_f32 v[228:229], v[210:211], s[54:55] op_sel_hi:[1,0]
	v_pk_mul_f32 v[230:231], v[212:213], s[54:55] op_sel_hi:[1,0]
	v_exp_f32_e32 v218, v218
	v_exp_f32_e32 v219, v219
	v_exp_f32_e32 v252, v252
	v_exp_f32_e32 v253, v253
	v_exp_f32_e32 v228, v228
	v_exp_f32_e32 v229, v229
	v_exp_f32_e32 v230, v230
	v_exp_f32_e32 v231, v231
	v_pk_add_f32 v[218:219], v[218:219], s[56:57] op_sel_hi:[1,0]
	v_pk_add_f32 v[252:253], v[252:253], s[56:57] op_sel_hi:[1,0]
	v_pk_add_f32 v[228:229], v[228:229], s[56:57] op_sel_hi:[1,0]
	v_pk_add_f32 v[230:231], v[230:231], s[56:57] op_sel_hi:[1,0]
	v_rcp_f32_e32 v218, v218
	v_rcp_f32_e32 v219, v219
	v_rcp_f32_e32 v252, v252
	v_rcp_f32_e32 v253, v253
	v_rcp_f32_e32 v228, v228
	v_rcp_f32_e32 v229, v229
	v_rcp_f32_e32 v230, v230
	v_rcp_f32_e32 v231, v231
	v_pk_mul_f32 v[142:143], v[142:143], v[218:219]
	v_pk_mul_f32 v[178:179], v[178:179], v[252:253]
	v_pk_mul_f32 v[210:211], v[210:211], v[228:229]
	v_pk_mul_f32 v[212:213], v[212:213], v[230:231]
	v_pk_fma_f32 v[218:219], v[198:199], v[82:83], v[226:227]
	v_pk_fma_f32 v[252:253], v[198:199], v[10:11], v[226:227]
	v_pk_fma_f32 v[228:229], v[198:199], v[2:3], v[226:227]
	v_pk_fma_f32 v[230:231], v[198:199], v[42:43], v[226:227]
	v_pk_fma_f32 v[218:219], v[206:207], v[10:11], v[218:219]
	v_pk_fma_f32 v[252:253], v[186:187], v[82:83], v[252:253]
	v_pk_fma_f32 v[228:229], v[186:187], v[10:11], v[228:229]
	v_pk_fma_f32 v[230:231], v[186:187], v[2:3], v[230:231]
	v_pk_fma_f32 v[252:253], v[206:207], v[2:3], v[252:253]
	v_pk_fma_f32 v[228:229], v[206:207], v[42:43], v[228:229]
	v_fmac_f32_dpp v218, v42, v186 row_shr:1 row_mask:0xf bank_mask:0xf bound_ctrl:1
	v_fmac_f32_dpp v230, v82, v206 row_shl:1 row_mask:0xf bank_mask:0xf bound_ctrl:1
	v_fmac_f32_dpp v219, v43, v187 row_shr:1 row_mask:0xf bank_mask:0xf bound_ctrl:1
	v_fmac_f32_dpp v231, v83, v207 row_shl:1 row_mask:0xf bank_mask:0xf bound_ctrl:1
	v_pk_mul_f32 v[142:143], v[142:143], v[218:219]
	v_pk_mul_f32 v[178:179], v[178:179], v[252:253]
	v_pk_mul_f32 v[210:211], v[210:211], v[228:229]
	v_pk_mul_f32 v[212:213], v[212:213], v[230:231]
	v_cvt_pk_bf16_f32 v239, v142, v143
	v_cvt_pk_bf16_f32 v243, v178, v179
	v_cvt_pk_bf16_f32 v247, v210, v211
	v_cvt_pk_bf16_f32 v251, v212, v213
	s_add_u32 s58, s28, 0x160000
	s_addc_u32 s59, s29, 0
	s_mov_b64 exec, s[12:13]
	global_store_dwordx4 v234, v[236:239], s[58:59]
	s_mov_b64 exec, -1
	s_add_u32 s58, s28, 0x162c00
	s_addc_u32 s59, s29, 0
	global_store_dwordx4 v234, v[240:243], s[58:59]
	s_add_u32 s58, s28, 0x165800
	s_addc_u32 s59, s29, 0
	global_store_dwordx4 v234, v[244:247], s[58:59]
	s_add_u32 s58, s28, 0x168400
	s_addc_u32 s59, s29, 0
	s_mov_b64 exec, s[10:11]
	global_store_dwordx4 v234, v[248:251], s[58:59]
	s_mov_b64 exec, -1
	s_andn2_b64 vcc, exec, s[52:53]
	s_mov_b64 s[52:53], -1
	s_cbranch_vccnz .LBB0_834
